# G1 tile order: each XCD owns 4 M-tiles and sweeps 8 N-tiles per round (XB tiles read by one XCD, 4 KiB contiguous C rows per round)
# speedup vs baseline: 1.0041x; 1.0041x over previous
.LBB0_335:
	s_ashr_i32 s0, s6, 3
	s_add_u32 s30, s56, 0x1c000000
	s_addc_u32 s31, s57, 0
	s_add_i32 s0, s7, s0
	s_ashr_i32 s6, s0, 31
	s_lshr_b32 s6, s6, 22
	s_add_i32 s6, s0, s6
	s_ashr_i32 s7, s6, 10
	s_and_b32 s6, s6, 0xfffffc00
	s_sub_i32 s6, s0, s6
	s_sext_i32_i16 s0, s6
	s_bfe_u32 s0, s0, 0x3001c
	s_add_i32 s9, s6, s0
	s_sext_i32_i16 s0, s9
	s_and_b32 s9, s9, 0xfff8
	s_sub_i32 s6, s6, s9
	s_lshl_b32 s7, s7, 3
	s_sext_i32_i16 s6, s6
	s_lshr_b32 s1, s3, 8
	s_lshr_b32 s0, s0, 3
	s_add_i32 s42, s7, s6
	s_and_b32 s42, s2, 3
	s_lshl_b32 s42, s42, 2
	s_bfe_u32 s6, s2, 0x20003
	s_add_i32 s42, s42, s6
	s_bfe_u32 s0, s2, 0x10002
	s_lshl_b32 s0, s0, 6
	s_lshr_b32 s6, s2, 5
	s_add_i32 s0, s0, s6
	s_lshr_b32 s8, s3, 6
	s_ashr_i32 s43, s42, 31
	s_bfe_i64 s[10:11], s[0:1], 0x100000
	s_lshl_b32 s33, s8, 10
	s_lshl_b64 s[6:7], s[42:43], 20
	s_lshl_b64 s[10:11], s[10:11], 20
	s_add_u32 s46, s56, s10
	s_addc_u32 s47, s57, s11
	s_add_i32 s34, s33, 0
	s_add_i32 m0, s34, 0x10000
	v_mov_b32_e32 v133, 0
	global_load_lds_dwordx4 v132, s[46:47]
	s_add_i32 m0, s34, 0x12000
	s_add_u32 s44, s30, s6
	global_load_lds_dwordx4 v136, s[46:47]
	s_addc_u32 s45, s31, s7
	s_mov_b32 m0, s34
	s_add_i32 s35, s34, 0x2000
	global_load_lds_dwordx4 v130, s[44:45]
	s_mov_b32 m0, s35
	s_add_u32 s6, s46, 0x80000
	global_load_lds_dwordx4 v134, s[44:45]
	s_addc_u32 s7, s47, 0
	s_add_i32 m0, s34, 0x14000
	v_mov_b32_e32 v137, v133
	global_load_lds_dwordx4 v132, s[6:7]
	s_add_i32 m0, s34, 0x16000
	v_mov_b32_e32 v131, v133
	global_load_lds_dwordx4 v136, s[6:7]
	s_add_u32 s6, s44, 0x80000
	s_addc_u32 s7, s45, 0
	s_add_i32 s43, s34, 0x4000
	s_mov_b32 m0, s43
	s_add_i32 s60, s34, 0x6000
	global_load_lds_dwordx4 v130, s[6:7]
	s_mov_b32 m0, s60
	v_mov_b32_e32 v135, v133
	global_load_lds_dwordx4 v134, s[6:7]
	s_mov_b32 s61, 0
	v_lshl_add_u64 v[8:9], s[46:47], 0, v[132:133]
	v_lshl_add_u64 v[6:7], s[46:47], 0, v[136:137]
	v_lshl_add_u64 v[4:5], s[44:45], 0, v[130:131]
	s_cmp_lg_u32 s1, 1
	v_lshl_add_u64 v[2:3], s[44:45], 0, v[134:135]
	s_cbranch_scc1 .LBB0_337
	s_barrier

.LBB0_338:
	s_add_i32 s61, s61, 1
	s_mul_i32 s0, s61, s64
	s_mul_hi_u32 s1, s61, s28
	s_add_i32 s1, s1, s0
	s_mul_i32 s0, s61, s28
	s_add_u32 s38, s0, s2
	s_addc_u32 s39, s1, s29
	v_cmp_gt_i64_e64 s[0:1], s[38:39], v[144:145]
	s_and_b64 vcc, exec, s[0:1]
	s_cbranch_vccnz .LBB0_344
	s_and_b32 s36, s2, 3
	s_lshl_b32 s36, s36, 2
	s_bfe_u32 s26, s2, 0x20003
	s_add_i32 s36, s36, s26
	s_bfe_u32 s26, s2, 0x10002
	s_lshl_b32 s26, s26, 6
	s_lshr_b32 s27, s2, 5
	s_add_i32 s26, s26, s27
	s_lshl_b32 s27, s61, 3
	s_add_i32 s26, s26, s27
